# attention item epilogue: the two pad nops between the convert / lane-swap stages removed (the stage order already gives the required wait states)
# speedup vs baseline: 1.0032x; 1.0032x over previous
.Lgq_skip:
	s_ashr_i32 s19, s18, 31
	s_lshl_b64 s[6:7], s[18:19], 14
	s_add_u32 s18, s6, s20
	s_addc_u32 s19, s7, s21
	s_lshl_b64 s[6:7], s[18:19], 5
	s_add_u32 s6, s24, s6
	s_addc_u32 s7, s25, s7
	s_lshl_b32 s9, s16, 2
	s_add_u32 s6, s6, s9
	s_addc_u32 s7, s7, 0
	s_lshl_b64 s[10:11], s[18:19], 10
	s_add_u32 s10, s22, s10
	s_addc_u32 s11, s23, s11
	s_lshl_b32 s9, s16, 7
	s_add_u32 s10, s10, s9
	s_addc_u32 s11, s11, 0
	v_mul_u32_u24_e32 v1, s14, v17
	v_lshlrev_b32_e32 v2, 10, v1
	v_lshl_add_u32 v2, v148, 5, v2
	v_lshlrev_b32_e32 v3, 5, v1
	v_cvt_pk_bf16_f32 v150, v134, v135
	v_cvt_pk_bf16_f32 v151, v136, v137
	v_cvt_pk_bf16_f32 v152, v130, v131
	v_cvt_pk_bf16_f32 v153, v132, v133
	v_cvt_pk_bf16_f32 v154, v126, v127
	v_cvt_pk_bf16_f32 v155, v128, v129
	v_cvt_pk_bf16_f32 v156, v122, v123
	v_cvt_pk_bf16_f32 v157, v124, v125
	v_cvt_pk_bf16_f32 v158, v114, v115
	v_cvt_pk_bf16_f32 v159, v116, v117
	v_cvt_pk_bf16_f32 v160, v106, v107
	v_cvt_pk_bf16_f32 v161, v108, v109
	v_cvt_pk_bf16_f32 v162, v110, v111
	v_cvt_pk_bf16_f32 v163, v112, v113
	v_cvt_pk_bf16_f32 v164, v102, v103
	v_cvt_pk_bf16_f32 v165, v104, v105
	v_permlane32_swap_b32_e32 v150, v154
	v_permlane32_swap_b32_e32 v152, v156
	v_permlane32_swap_b32_e32 v151, v155
	v_permlane32_swap_b32_e32 v153, v157
	v_permlane32_swap_b32_e32 v158, v162
	v_permlane32_swap_b32_e32 v160, v164
	v_permlane32_swap_b32_e32 v159, v163
	v_permlane32_swap_b32_e32 v161, v165
	v_permlane16_swap_b32_e32 v150, v152
	v_permlane16_swap_b32_e32 v154, v156
	v_permlane16_swap_b32_e32 v151, v153
	v_permlane16_swap_b32_e32 v155, v157
	v_permlane16_swap_b32_e32 v158, v160
	v_permlane16_swap_b32_e32 v162, v164
	v_permlane16_swap_b32_e32 v159, v161
	v_permlane16_swap_b32_e32 v163, v165
	global_store_dwordx4 v2, v[150:153], s[10:11]
	global_store_dwordx4 v2, v[154:157], s[10:11] offset:16
	s_lshl_b32 s9, s14, 14
	s_add_u32 s10, s10, s9
	s_addc_u32 s11, s11, 0
	global_store_dwordx4 v2, v[158:161], s[10:11]
	global_store_dwordx4 v2, v[162:165], s[10:11] offset:16
	v_cmp_eq_u32_e32 vcc, 0, v148
	s_and_saveexec_b64 s[34:35], vcc
	global_store_dword v3, v138, s[6:7]
	s_lshl_b32 s9, s14, 9
	s_add_u32 s6, s6, s9
	s_addc_u32 s7, s7, 0
	global_store_dword v3, v118, s[6:7]
	s_or_b64 exec, exec, s[34:35]
	s_branch .LBB0_331
